# scan stepper: per-wave start skew of each chunk (waves 1-3 delayed by 1-3 short nop loops) so the four stepper waves' LDS bursts do not collide; confirmed with scan phases repeated 4x
# baseline (speedup 1.0000x reference)
.Lst_chunk:
	s_mov_b32 s0, s6
	s_cmp_eq_u32 s0, 0
	s_cbranch_scc1 .Lst_noskewA
.Lst_skewA:
	s_nop 11
	s_add_i32 s0, s0, -1
	s_cmp_lg_u32 s0, 0
	s_cbranch_scc1 .Lst_skewA
